# scan stages B/C: two late LDS reads issued at stage start
# speedup vs baseline: 1.0049x; 1.0049x over previous
.LBB0_1494:
	s_or_b64 exec, exec, s[2:3]
	v_cvt_pk_bf16_f32 v62, v64, v65
	v_cvt_pk_bf16_f32 v63, v60, v61
	ds_write_b64 v137, v[62:63]
	v_cvt_pk_bf16_f32 v60, v76, v77
	v_cvt_pk_bf16_f32 v61, v78, v79
	v_cvt_pk_bf16_f32 v62, v80, v81
	v_cvt_pk_bf16_f32 v63, v82, v83
	ds_write2_b64 v134, v[60:61], v[62:63] offset1:4
	v_cvt_pk_bf16_f32 v60, v84, v85
	v_cvt_pk_bf16_f32 v61, v86, v87
	v_cvt_pk_bf16_f32 v62, v88, v89
	v_cvt_pk_bf16_f32 v63, v90, v91
	ds_write2_b64 v134, v[60:61], v[62:63] offset0:8 offset1:12
	v_add_u32_e32 v60, v163, v160
	s_waitcnt lgkmcnt(0)
	s_barrier
	ds_read_b128 v[62:65], v60
	ds_read_b128 v[76:79], v132
	ds_read_b128 v[80:83], v133
	ds_read_b128 v[84:87], v60 offset:64
	s_waitcnt lgkmcnt(0)
	v_mfma_f32_16x16x32_bf16 v[76:79], v[62:65], v[76:79], 0
	v_add_u32_e32 v61, s64, v125
	ds_read_b128 v[240:243], v61
	s_and_b64 s[2:3], s[0:1], exec
	s_mov_b32 s2, 0x23100
	v_mfma_f32_16x16x32_bf16 v[62:65], v[62:65], v[80:83], 0
	ds_read_b128 v[80:83], v130
	ds_read_b128 v[88:91], v131
	s_cselect_b32 s2, s2, 0x8800
	s_waitcnt lgkmcnt(0)
	v_mfma_f32_16x16x32_bf16 v[76:79], v[84:87], v[80:83], v[76:79]
	ds_read_b128 v[80:83], v60 offset:128
	v_mfma_f32_16x16x32_bf16 v[62:65], v[84:87], v[88:91], v[62:65]
	ds_read_b128 v[84:87], v128
	ds_read_b128 v[88:91], v129
	s_waitcnt lgkmcnt(0)
	v_mfma_f32_16x16x32_bf16 v[76:79], v[80:83], v[84:87], v[76:79]
	ds_read_b128 v[84:87], v60 offset:192
	v_mfma_f32_16x16x32_bf16 v[62:65], v[80:83], v[88:91], v[62:65]
	ds_read_b128 v[80:83], v126
	ds_read_b128 v[88:91], v127
	s_waitcnt lgkmcnt(0)
	v_mfma_f32_16x16x32_bf16 v[76:79], v[84:87], v[80:83], v[76:79]
	s_waitcnt lgkmcnt(0)
	v_sub_f32_e32 v61, v194, v240
	v_mul_f32_e32 v61, 0x3fb8aa3b, v61
	v_exp_f32_e32 v80, v61
	v_sub_f32_e32 v61, v194, v241
	v_mul_f32_e32 v61, 0x3fb8aa3b, v61
	v_exp_f32_e32 v81, v61
	v_sub_f32_e32 v61, v194, v242
	v_mul_f32_e32 v61, 0x3fb8aa3b, v61
	v_exp_f32_e32 v82, v61
	v_sub_f32_e32 v61, v194, v243
	v_mul_f32_e32 v61, 0x3fb8aa3b, v61
	v_mfma_f32_16x16x32_bf16 v[64:67], v[84:87], v[88:91], v[62:65]
	v_exp_f32_e32 v83, v61
	v_sub_f32_e32 v73, v73, v77
	v_sub_f32_e32 v72, v72, v76
	v_sub_f32_e32 v63, v75, v79
	v_sub_f32_e32 v62, v74, v78
	v_pk_mul_f32 v[74:75], v[72:73], v[80:81]
	v_pk_mul_f32 v[76:77], v[62:63], v[82:83]
	v_cvt_pk_bf16_f32 v72, v72, v73
	v_cvt_pk_bf16_f32 v73, v62, v63
	v_add_u32_e32 v62, v170, v164
	v_sub_f32_e32 v67, v71, v67
	v_sub_f32_e32 v66, v70, v66
	v_sub_f32_e32 v65, v69, v65
	v_sub_f32_e32 v64, v68, v64
	ds_write_b64 v62, v[72:73]
	v_cvt_pk_bf16_f32 v72, v74, v75
	v_cvt_pk_bf16_f32 v73, v76, v77
	v_pk_mul_f32 v[68:69], v[64:65], v[80:81]
	v_pk_mul_f32 v[70:71], v[66:67], v[82:83]
	v_cvt_pk_bf16_f32 v64, v64, v65
	v_cvt_pk_bf16_f32 v65, v66, v67
	v_add_u32_e32 v63, v171, v164
	ds_write_b64 v124, v[72:73]
	ds_write_b64 v63, v[64:65]
	v_cvt_pk_bf16_f32 v64, v68, v69
	v_cvt_pk_bf16_f32 v65, v70, v71
	ds_write_b64 v123, v[64:65]
	v_add_u32_e32 v64, v170, v160
	s_waitcnt lgkmcnt(0)
	s_barrier
	ds_read_b128 v[66:69], v64
	ds_read_b32 v244, v195
	v_add_u32_e32 v61, v162, v160
	v_add_u32_e32 v65, v171, v160
	v_mul_f32_e32 v86, 0x3fb8aa3b, v194
	ds_read_b128 v[70:73], v61
	ds_read_b128 v[74:77], v65
	ds_read_b128 v[78:81], v193
	ds_read_b128 v[82:85], v193 offset:2304
	v_exp_f32_e32 v90, v86
	ds_read_b128 v[86:89], v120
	s_waitcnt lgkmcnt(0)
	v_mfma_f32_16x16x32_bf16 v[66:69], v[66:69], v[70:73], 0
	v_mul_f32_e64 v2, v2, v90
	v_mul_f32_e64 v3, v3, v90
	v_pk_mul_f32 v[0:1], v[0:1], v[90:91] op_sel_hi:[1,0]
	v_pk_mul_f32 v[10:11], v[10:11], v[90:91] op_sel_hi:[1,0]
	v_mfma_f32_16x16x32_bf16 v[70:73], v[74:77], v[70:73], 0
	ds_read_b128 v[74:77], v193 offset:4608
	v_pk_mul_f32 v[8:9], v[8:9], v[90:91] op_sel_hi:[1,0]
	v_pk_mul_f32 v[6:7], v[6:7], v[90:91] op_sel_hi:[1,0]
	v_mfma_f32_16x16x32_bf16 v[0:3], v[78:81], v[86:89], v[0:3]
	ds_read_b128 v[78:81], v193 offset:6912
	v_pk_mul_f32 v[4:5], v[4:5], v[90:91] op_sel_hi:[1,0]
	v_pk_mul_f32 v[14:15], v[14:15], v[90:91] op_sel_hi:[1,0]
	v_pk_mul_f32 v[12:13], v[12:13], v[90:91] op_sel_hi:[1,0]
	v_mfma_f32_16x16x32_bf16 v[8:11], v[82:85], v[86:89], v[8:11]
	ds_read_b128 v[82:85], v122
	s_waitcnt lgkmcnt(0)
	v_mfma_f32_16x16x32_bf16 v[4:7], v[74:77], v[86:89], v[4:7]
	ds_read_b128 v[74:77], v61 offset:64
	v_mfma_f32_16x16x32_bf16 v[12:15], v[78:81], v[86:89], v[12:15]
	ds_read_b128 v[78:81], v121
	s_waitcnt lgkmcnt(0)
	v_mfma_f32_16x16x32_bf16 v[66:69], v[82:85], v[74:77], v[66:69]
	ds_read_b128 v[82:85], v193 offset:64
	ds_read_b128 v[86:89], v120 offset:64
	v_mfma_f32_16x16x32_bf16 v[70:73], v[78:81], v[74:77], v[70:73]
	ds_read_b128 v[74:77], v193 offset:2368
	ds_read_b128 v[78:81], v193 offset:4672
	s_waitcnt lgkmcnt(0)
	v_mfma_f32_16x16x32_bf16 v[8:11], v[74:77], v[86:89], v[8:11]
	ds_read_b128 v[74:77], v193 offset:6976
	v_mfma_f32_16x16x32_bf16 v[4:7], v[78:81], v[86:89], v[4:7]
	s_waitcnt lgkmcnt(0)
	v_mfma_f32_16x16x32_bf16 v[12:15], v[74:77], v[86:89], v[12:15]
	v_mul_f32_e32 v74, 0x3fb8aa3b, v244
	v_exp_f32_e32 v74, v74
	v_lshl_add_u32 v76, s63, 6, v93
	v_mfma_f32_16x16x32_bf16 v[0:3], v[82:85], v[86:89], v[0:3]
	v_ashrrev_i32_e32 v77, 31, v76
	v_lshlrev_b64 v[76:77], 10, v[76:77]
	v_pk_fma_f32 v[54:55], v[54:55], v[74:75], v[68:69] op_sel_hi:[1,0,1]
	v_pk_fma_f32 v[52:53], v[52:53], v[74:75], v[66:67] op_sel_hi:[1,0,1]
	v_pk_fma_f32 v[56:57], v[56:57], v[74:75], v[70:71] op_sel_hi:[1,0,1]
	v_cvt_pk_bf16_f32 v52, v52, v53
	v_cvt_pk_bf16_f32 v53, v54, v55
	v_lshl_add_u64 v[54:55], v[116:117], 0, v[76:77]
	s_waitcnt vmcnt(0)
	global_store_dwordx2 v[54:55], v[52:53], off
	v_pk_fma_f32 v[52:53], v[58:59], v[74:75], v[72:73] op_sel_hi:[1,0,1]
	v_cvt_pk_bf16_f32 v56, v56, v57
	v_cvt_pk_bf16_f32 v57, v52, v53
	v_cvt_pk_bf16_f32 v52, v0, v1
	v_cvt_pk_bf16_f32 v53, v2, v3
	global_store_dwordx2 v[54:55], v[56:57], off offset:32
	ds_write_b64 v119, v[52:53]
	v_cvt_pk_bf16_f32 v52, v8, v9
	v_cvt_pk_bf16_f32 v53, v10, v11
	ds_write_b64 v118, v[52:53]
	v_cvt_pk_bf16_f32 v52, v4, v5
	v_cvt_pk_bf16_f32 v53, v6, v7
	ds_write_b64 v111, v[52:53]
	v_cvt_pk_bf16_f32 v52, v12, v13
	v_cvt_pk_bf16_f32 v53, v14, v15
	ds_write_b64 v97, v[52:53]
	v_add_u32_e32 v52, s2, v165
	ds_write_b128 v150, v[16:19]
	ds_write_b128 v151, v[20:23] offset:17408
	v_add_u32_e32 v16, v52, v152
	ds_write_b128 v16, v[24:27]
	ds_write_b128 v153, v[28:31]
	ds_write_b128 v154, v[32:35] offset:17408
	v_add_u32_e32 v16, v52, v155
	ds_write_b128 v16, v[36:39]
	ds_write_b128 v156, v[40:43] offset:53248
	ds_write_b128 v156, v[44:47] offset:62464
	ds_write_b128 v157, v[48:51]
	s_and_saveexec_b64 s[2:3], s[60:61]
	s_cbranch_execz .LBB0_1471
	s_and_b64 s[0:1], s[0:1], exec
	s_cselect_b32 s0, 0x27900, s89
	v_add_u32_e32 v16, s0, v158
	ds_write_b32 v16, v149
	s_branch .LBB0_1471
